# v3 + gate/up GEMM K-loop: LDS-DMA loads use SGPR base + 32-bit VGPR offset (no 64-bit VALU address adds)
# speedup vs baseline: 1.0101x; 1.0101x over previous
; #define PG8_STAGE(bufoff, gbase, voff) do { _Pragma("unroll") for (int _i = 0; _i < 2; ++_i) \
;         __builtin_amdgcn_global_load_lds((const unsigned*)((const char*)(gbase) + (voff)[_i]), (PG8_LAS unsigned*)(lds + (bufoff) + ldsw + _i * 8192), 16, 0, 0); } while (0)
; #define PG8_LDA(dst, b, h) do { _Pragma("unroll") for (int m = 0; m < 4; ++m) _Pragma("unroll") for (int k = 0; k < 2; ++k) dst[m][k] = *(const PG8_LAS bf16x8*)(lds + PG8_SA(b, h) + aoff + m * 2048 + k * 1024); } while (0)
; #define PG8_LDB(dst, b, h) do { _Pragma("unroll") for (int n = 0; n < 2; ++n) _Pragma("unroll") for (int k = 0; k < 2; ++k) dst[n][k] = *(const PG8_LAS bf16x8*)(lds + PG8_SB(b, h) + boff + n * 2048 + k * 1024); } while (0)
; #define PG8_MMA(ai, bj, At, Bt) do { __builtin_amdgcn_s_setprio(1); _Pragma("unroll") for (int m = 0; m < 4; ++m) _Pragma("unroll") for (int n = 0; n < 2; ++n) _Pragma("unroll") for (int k = 0; k < 2; ++k) \
;         acc[ai][bj][m][n] = __builtin_amdgcn_mfma_f32_16x16x32_bf16(Bt[n][k], At[m][k], acc[ai][bj][m][n], 0, 0, 0); __builtin_amdgcn_s_setprio(0); } while (0)
; #define PG8_WAIT_V(n) asm volatile("s_waitcnt vmcnt(" #n ")" ::: "memory")
; #define PG8_WAIT_L(n) asm volatile("s_waitcnt lgkmcnt(" #n ")" ::: "memory")
; #define PG8_BAR __builtin_amdgcn_s_barrier()
; #define PG8_SCHED __builtin_amdgcn_sched_barrier(0)
; template <class Epi, class Sched, bool ALIGN_EPI = false, bool SP2 = false>
; __device__ __forceinline__ void gemm_phase(PG8_LAS unsigned char* lds, const Gemm g, const Sched& S, const Epi& E) {
;     ...
;             PG8_LDB(B0, 0, 0); PG8_LDB(B1, 0, 1); PG8_SCHED; PG8_LDA(At, 0, 0); PG8_STAGE(PG8_SA(1, 1), a1 + hstep, voffA);
;             PG8_WAIT_V(8); PG8_WAIT_L(0); PG8_BAR; PG8_MMA(0, 0, At, B0); PG8_MMA(0, 1, At, B1); PG8_BAR; PG8_SCHED;
;             PG8_LDA(At, 0, 1); PG8_STAGE(PG8_SB(0, 0), b2, voffB); PG8_STAGE(PG8_SB(0, 1), b2 + hstep, voffB); PG8_STAGE(PG8_SA(0, 0), a2, voffA);
;             PG8_WAIT_V(8); PG8_WAIT_L(0); PG8_BAR; PG8_MMA(1, 0, At, B0); PG8_MMA(1, 1, At, B1); PG8_BAR; PG8_SCHED;
;             PG8_LDB(B0, 1, 0); PG8_LDB(B1, 1, 1); PG8_SCHED; PG8_LDA(At, 1, 0); PG8_STAGE(PG8_SA(0, 1), a2 + hstep, voffA);
;             PG8_WAIT_V(8); PG8_WAIT_L(0); PG8_BAR; PG8_MMA(0, 0, At, B0); PG8_MMA(0, 1, At, B1); PG8_BAR; PG8_SCHED;
.LBB0_493:
	s_add_u32 s24, s22, 0xfffc0080
	s_addc_u32 s25, s23, -1
	s_add_i32 s51, 0, 0x10000
	s_cmp_eq_u32 s50, 12
	s_cselect_b32 s27, s17, s25
	s_cselect_b32 s26, s46, s24
	v_add_u32_e32 v146, s51, v149
	s_cselect_b32 s25, s15, s49
	s_cselect_b32 s24, s47, s48
	s_add_i32 s54, 0, 0x14000
	ds_read_b128 v[142:145], v146
	ds_read_b128 v[152:155], v146 offset:1024
	ds_read_b128 v[172:175], v146 offset:2048
	ds_read_b128 v[176:179], v146 offset:3072
	v_add_u32_e32 v146, s54, v149
	ds_read_b128 v[180:183], v146
	ds_read_b128 v[184:187], v146 offset:1024
	ds_read_b128 v[188:191], v146 offset:2048
	ds_read_b128 v[192:195], v146 offset:3072
	s_add_i32 m0, s30, 0xc000
	ds_read_b128 v[196:199], v151
	ds_read_b128 v[214:217], v151 offset:1024
	ds_read_b128 v[218:221], v151 offset:2048
	ds_read_b128 v[222:225], v151 offset:3072
	ds_read_b128 v[226:229], v151 offset:4096
	ds_read_b128 v[230:233], v151 offset:5120
	ds_read_b128 v[234:237], v151 offset:6144
	ds_read_b128 v[238:241], v151 offset:7168
	global_load_lds_dwordx4 v138, s[22:23]
	s_add_i32 m0, s30, 0xe000
	s_nop 0
	global_load_lds_dwordx4 v140, s[22:23]
	s_waitcnt vmcnt(8)
	s_waitcnt lgkmcnt(0)
	s_barrier
	s_setprio 1
	s_waitcnt lgkmcnt(0)
	v_mfma_f32_16x16x32_bf16 v[126:129], v[142:145], v[196:199], v[126:129]
	v_mfma_f32_16x16x32_bf16 v[118:121], v[172:175], v[196:199], v[118:121]
	v_mfma_f32_16x16x32_bf16 v[110:113], v[142:145], v[218:221], v[110:113]
	v_mfma_f32_16x16x32_bf16 v[102:105], v[172:175], v[218:221], v[102:105]
	v_mfma_f32_16x16x32_bf16 v[94:97], v[142:145], v[226:229], v[94:97]
	v_mfma_f32_16x16x32_bf16 v[86:89], v[172:175], v[226:229], v[86:89]
	v_mfma_f32_16x16x32_bf16 v[78:81], v[142:145], v[234:237], v[78:81]
	v_mfma_f32_16x16x32_bf16 v[70:73], v[172:175], v[234:237], v[70:73]
	v_mfma_f32_16x16x32_bf16 v[126:129], v[152:155], v[214:217], v[126:129]
	v_mfma_f32_16x16x32_bf16 v[118:121], v[176:179], v[214:217], v[118:121]
	v_mfma_f32_16x16x32_bf16 v[110:113], v[152:155], v[222:225], v[110:113]
	v_mfma_f32_16x16x32_bf16 v[102:105], v[176:179], v[222:225], v[102:105]
	v_mfma_f32_16x16x32_bf16 v[94:97], v[152:155], v[230:233], v[94:97]
	v_mfma_f32_16x16x32_bf16 v[86:89], v[176:179], v[230:233], v[86:89]
	v_mfma_f32_16x16x32_bf16 v[78:81], v[152:155], v[238:241], v[78:81]
	v_mfma_f32_16x16x32_bf16 v[70:73], v[176:179], v[238:241], v[70:73]
	s_setprio 0
	s_setprio 1
	v_mfma_f32_16x16x32_bf16 v[122:125], v[180:183], v[196:199], v[122:125]
	v_mfma_f32_16x16x32_bf16 v[114:117], v[188:191], v[196:199], v[114:117]
	v_mfma_f32_16x16x32_bf16 v[106:109], v[180:183], v[218:221], v[106:109]
	v_mfma_f32_16x16x32_bf16 v[98:101], v[188:191], v[218:221], v[98:101]
	v_mfma_f32_16x16x32_bf16 v[90:93], v[180:183], v[226:229], v[90:93]
	v_mfma_f32_16x16x32_bf16 v[82:85], v[188:191], v[226:229], v[82:85]
	v_mfma_f32_16x16x32_bf16 v[74:77], v[180:183], v[234:237], v[74:77]
	v_mfma_f32_16x16x32_bf16 v[66:69], v[188:191], v[234:237], v[66:69]
	v_mfma_f32_16x16x32_bf16 v[122:125], v[184:187], v[214:217], v[122:125]
	v_mfma_f32_16x16x32_bf16 v[114:117], v[192:195], v[214:217], v[114:117]
	v_mfma_f32_16x16x32_bf16 v[106:109], v[184:187], v[222:225], v[106:109]
	v_mfma_f32_16x16x32_bf16 v[98:101], v[192:195], v[222:225], v[98:101]
	v_mfma_f32_16x16x32_bf16 v[90:93], v[184:187], v[230:233], v[90:93]
	v_mfma_f32_16x16x32_bf16 v[82:85], v[192:195], v[230:233], v[82:85]
	v_mfma_f32_16x16x32_bf16 v[74:77], v[184:187], v[238:241], v[74:77]
	v_mfma_f32_16x16x32_bf16 v[66:69], v[192:195], v[238:241], v[66:69]
	s_setprio 0
	s_barrier
	s_add_i32 s51, s51, s2
	s_mov_b32 m0, s51
	ds_read_b128 v[196:199], v151 offset:16384
	ds_read_b128 v[214:217], v151 offset:17408
	ds_read_b128 v[218:221], v151 offset:18432
	ds_read_b128 v[222:225], v151 offset:19456
	ds_read_b128 v[226:229], v151 offset:20480
	ds_read_b128 v[230:233], v151 offset:21504
	ds_read_b128 v[234:237], v151 offset:22528
	ds_read_b128 v[238:241], v151 offset:23552
	global_load_lds_dwordx4 v0, s[24:25]
	s_add_i32 m0, s51, 0x2000
	s_add_u32 s52, s24, 0x40000
	s_addc_u32 s53, s25, 0
	s_add_i32 s51, s54, s2
	global_load_lds_dwordx4 v130, s[24:25]
	s_mov_b32 m0, s51
	s_nop 0
	global_load_lds_dwordx4 v0, s[52:53]
	s_add_i32 m0, s51, 0x2000
	s_nop 0
	global_load_lds_dwordx4 v130, s[52:53]
	s_mov_b32 m0, s30
	s_nop 0
	global_load_lds_dwordx4 v134, s[26:27]
	s_mov_b32 m0, s31
	s_nop 0
	global_load_lds_dwordx4 v132, s[26:27]
	s_waitcnt vmcnt(8)
	s_waitcnt lgkmcnt(0)
	s_barrier
	s_setprio 1
	s_waitcnt lgkmcnt(0)
	v_mfma_f32_16x16x32_bf16 v[62:65], v[142:145], v[196:199], v[62:65]
	v_mfma_f32_16x16x32_bf16 v[54:57], v[172:175], v[196:199], v[54:57]
	v_mfma_f32_16x16x32_bf16 v[46:49], v[142:145], v[218:221], v[46:49]
	v_mfma_f32_16x16x32_bf16 v[38:41], v[172:175], v[218:221], v[38:41]
	v_mfma_f32_16x16x32_bf16 v[30:33], v[142:145], v[226:229], v[30:33]
	v_mfma_f32_16x16x32_bf16 v[22:25], v[172:175], v[226:229], v[22:25]
	v_mfma_f32_16x16x32_bf16 v[14:17], v[142:145], v[234:237], v[14:17]
	v_mfma_f32_16x16x32_bf16 v[6:9], v[172:175], v[234:237], v[6:9]
	v_mfma_f32_16x16x32_bf16 v[62:65], v[152:155], v[214:217], v[62:65]
	v_mfma_f32_16x16x32_bf16 v[54:57], v[176:179], v[214:217], v[54:57]
	v_mfma_f32_16x16x32_bf16 v[46:49], v[152:155], v[222:225], v[46:49]
	v_mfma_f32_16x16x32_bf16 v[38:41], v[176:179], v[222:225], v[38:41]
	v_mfma_f32_16x16x32_bf16 v[30:33], v[152:155], v[230:233], v[30:33]
	v_mfma_f32_16x16x32_bf16 v[22:25], v[176:179], v[230:233], v[22:25]
	v_mfma_f32_16x16x32_bf16 v[14:17], v[152:155], v[238:241], v[14:17]
	v_mfma_f32_16x16x32_bf16 v[6:9], v[176:179], v[238:241], v[6:9]
	s_setprio 0
	s_setprio 1
	v_mfma_f32_16x16x32_bf16 v[58:61], v[180:183], v[196:199], v[58:61]
	v_mfma_f32_16x16x32_bf16 v[50:53], v[188:191], v[196:199], v[50:53]
	v_mfma_f32_16x16x32_bf16 v[42:45], v[180:183], v[218:221], v[42:45]
	v_mfma_f32_16x16x32_bf16 v[34:37], v[188:191], v[218:221], v[34:37]
	v_mfma_f32_16x16x32_bf16 v[26:29], v[180:183], v[226:229], v[26:29]
	v_mfma_f32_16x16x32_bf16 v[18:21], v[188:191], v[226:229], v[18:21]
	v_mfma_f32_16x16x32_bf16 v[10:13], v[180:183], v[234:237], v[10:13]
	v_mfma_f32_16x16x32_bf16 v[2:5], v[188:191], v[234:237], v[2:5]
	v_mfma_f32_16x16x32_bf16 v[58:61], v[184:187], v[214:217], v[58:61]
	v_mfma_f32_16x16x32_bf16 v[50:53], v[192:195], v[214:217], v[50:53]
	v_mfma_f32_16x16x32_bf16 v[42:45], v[184:187], v[222:225], v[42:45]
	v_mfma_f32_16x16x32_bf16 v[34:37], v[192:195], v[222:225], v[34:37]
	v_mfma_f32_16x16x32_bf16 v[26:29], v[184:187], v[230:233], v[26:29]
	v_mfma_f32_16x16x32_bf16 v[18:21], v[192:195], v[230:233], v[18:21]
	v_mfma_f32_16x16x32_bf16 v[10:13], v[184:187], v[238:241], v[10:13]
	v_mfma_f32_16x16x32_bf16 v[2:5], v[192:195], v[238:241], v[2:5]
	s_setprio 0
	s_barrier
; #define PG8_STAGE(bufoff, gbase, voff) do { _Pragma("unroll") for (int _i = 0; _i < 2; ++_i) \
;         __builtin_amdgcn_global_load_lds((const unsigned*)((const char*)(gbase) + (voff)[_i]), (PG8_LAS unsigned*)(lds + (bufoff) + ldsw + _i * 8192), 16, 0, 0); } while (0)
; #define PG8_LDA(dst, b, h) do { _Pragma("unroll") for (int m = 0; m < 4; ++m) _Pragma("unroll") for (int k = 0; k < 2; ++k) dst[m][k] = *(const PG8_LAS bf16x8*)(lds + PG8_SA(b, h) + aoff + m * 2048 + k * 1024); } while (0)
; #define PG8_MMA(ai, bj, At, Bt) do { __builtin_amdgcn_s_setprio(1); _Pragma("unroll") for (int m = 0; m < 4; ++m) _Pragma("unroll") for (int n = 0; n < 2; ++n) _Pragma("unroll") for (int k = 0; k < 2; ++k) \
;         acc[ai][bj][m][n] = __builtin_amdgcn_mfma_f32_16x16x32_bf16(Bt[n][k], At[m][k], acc[ai][bj][m][n], 0, 0, 0); __builtin_amdgcn_s_setprio(0); } while (0)
; #define PG8_WAIT_V(n) asm volatile("s_waitcnt vmcnt(" #n ")" ::: "memory")
; #define PG8_WAIT_L(n) asm volatile("s_waitcnt lgkmcnt(" #n ")" ::: "memory")
; #define PG8_BAR __builtin_amdgcn_s_barrier()
; #define PG8_SCHED __builtin_amdgcn_sched_barrier(0)
; template <class Epi, class Sched, bool ALIGN_EPI = false, bool SP2 = false>
; __device__ __forceinline__ void gemm_phase(PG8_LAS unsigned char* lds, const Gemm g, const Sched& S, const Epi& E) {
;     ...
;             PG8_WAIT_V(8); PG8_WAIT_L(0); PG8_BAR; PG8_MMA(0, 0, At, B0); PG8_MMA(0, 1, At, B1); PG8_BAR; PG8_SCHED;
;             PG8_LDA(At, 1, 1); PG8_STAGE(PG8_SB(1, 0), b3, voffB); PG8_STAGE(PG8_SB(1, 1), b3 + hstep, voffB); PG8_STAGE(PG8_SA(1, 0), a3, voffA);
;             PG8_WAIT_V(8); PG8_WAIT_L(0); PG8_BAR; PG8_MMA(1, 0, At, B0); PG8_MMA(1, 1, At, B1); PG8_BAR; PG8_SCHED;
	s_add_i32 s51, 0, 0x18000
	v_add_u32_e32 v158, s51, v149
	s_add_i32 s52, 0, 0x1c000
	ds_read_b128 v[142:145], v158
	ds_read_b128 v[152:155], v158 offset:1024
	ds_read_b128 v[172:175], v158 offset:2048
	ds_read_b128 v[176:179], v158 offset:3072
	v_add_u32_e32 v158, s52, v149
	ds_read_b128 v[180:183], v158
	ds_read_b128 v[184:187], v158 offset:1024
	ds_read_b128 v[188:191], v158 offset:2048
	ds_read_b128 v[192:195], v158 offset:3072
	s_add_u32 s26, s26, 0x40000
	s_addc_u32 s27, s27, 0
	s_mov_b32 m0, s34
	ds_read_b128 v[196:199], v151 offset:32768
	ds_read_b128 v[214:217], v151 offset:33792
	ds_read_b128 v[218:221], v151 offset:34816
	ds_read_b128 v[222:225], v151 offset:35840
	ds_read_b128 v[226:229], v151 offset:36864
	ds_read_b128 v[230:233], v151 offset:37888
	ds_read_b128 v[234:237], v151 offset:38912
	ds_read_b128 v[238:241], v151 offset:39936
	global_load_lds_dwordx4 v134, s[26:27]
	s_mov_b32 m0, s35
	s_nop 0
	global_load_lds_dwordx4 v132, s[26:27]
	s_waitcnt vmcnt(8)
	s_waitcnt lgkmcnt(0)
	s_barrier
	s_setprio 1
	s_waitcnt lgkmcnt(0)
	v_mfma_f32_16x16x32_bf16 v[126:129], v[142:145], v[196:199], v[126:129]
	v_mfma_f32_16x16x32_bf16 v[118:121], v[172:175], v[196:199], v[118:121]
	v_mfma_f32_16x16x32_bf16 v[110:113], v[142:145], v[218:221], v[110:113]
	v_mfma_f32_16x16x32_bf16 v[102:105], v[172:175], v[218:221], v[102:105]
	v_mfma_f32_16x16x32_bf16 v[94:97], v[142:145], v[226:229], v[94:97]
	v_mfma_f32_16x16x32_bf16 v[86:89], v[172:175], v[226:229], v[86:89]
	v_mfma_f32_16x16x32_bf16 v[78:81], v[142:145], v[234:237], v[78:81]
	v_mfma_f32_16x16x32_bf16 v[70:73], v[172:175], v[234:237], v[70:73]
	v_mfma_f32_16x16x32_bf16 v[126:129], v[152:155], v[214:217], v[126:129]
	v_mfma_f32_16x16x32_bf16 v[118:121], v[176:179], v[214:217], v[118:121]
	v_mfma_f32_16x16x32_bf16 v[110:113], v[152:155], v[222:225], v[110:113]
	v_mfma_f32_16x16x32_bf16 v[102:105], v[176:179], v[222:225], v[102:105]
	v_mfma_f32_16x16x32_bf16 v[94:97], v[152:155], v[230:233], v[94:97]
	v_mfma_f32_16x16x32_bf16 v[86:89], v[176:179], v[230:233], v[86:89]
	v_mfma_f32_16x16x32_bf16 v[78:81], v[152:155], v[238:241], v[78:81]
	v_mfma_f32_16x16x32_bf16 v[70:73], v[176:179], v[238:241], v[70:73]
	s_setprio 0
	s_setprio 1
	v_mfma_f32_16x16x32_bf16 v[122:125], v[180:183], v[196:199], v[122:125]
	v_mfma_f32_16x16x32_bf16 v[114:117], v[188:191], v[196:199], v[114:117]
	v_mfma_f32_16x16x32_bf16 v[106:109], v[180:183], v[218:221], v[106:109]
	v_mfma_f32_16x16x32_bf16 v[98:101], v[188:191], v[218:221], v[98:101]
	v_mfma_f32_16x16x32_bf16 v[90:93], v[180:183], v[226:229], v[90:93]
	v_mfma_f32_16x16x32_bf16 v[82:85], v[188:191], v[226:229], v[82:85]
	v_mfma_f32_16x16x32_bf16 v[74:77], v[180:183], v[234:237], v[74:77]
	v_mfma_f32_16x16x32_bf16 v[66:69], v[188:191], v[234:237], v[66:69]
	v_mfma_f32_16x16x32_bf16 v[122:125], v[184:187], v[214:217], v[122:125]
	v_mfma_f32_16x16x32_bf16 v[114:117], v[192:195], v[214:217], v[114:117]
	v_mfma_f32_16x16x32_bf16 v[106:109], v[184:187], v[222:225], v[106:109]
	v_mfma_f32_16x16x32_bf16 v[98:101], v[192:195], v[222:225], v[98:101]
	v_mfma_f32_16x16x32_bf16 v[90:93], v[184:187], v[230:233], v[90:93]
	v_mfma_f32_16x16x32_bf16 v[82:85], v[192:195], v[230:233], v[82:85]
	v_mfma_f32_16x16x32_bf16 v[74:77], v[184:187], v[238:241], v[74:77]
	v_mfma_f32_16x16x32_bf16 v[66:69], v[192:195], v[238:241], v[66:69]
	s_setprio 0
	s_barrier
	s_add_u32 s98, s26, 0xfffc0080
	s_addc_u32 s99, s27, -1
	s_add_i32 s26, s51, s2
	s_add_u32 s100, s24, 0x80
	s_addc_u32 s101, s25, 0
	s_mov_b32 m0, s26
	ds_read_b128 v[196:199], v151 offset:49152
	ds_read_b128 v[214:217], v151 offset:50176
	ds_read_b128 v[218:221], v151 offset:51200
	ds_read_b128 v[222:225], v151 offset:52224
	ds_read_b128 v[226:229], v151 offset:53248
	ds_read_b128 v[230:233], v151 offset:54272
	ds_read_b128 v[234:237], v151 offset:55296
	ds_read_b128 v[238:241], v151 offset:56320
	global_load_lds_dwordx4 v0, s[100:101]
	s_add_i32 m0, s26, 0x2000
	s_add_u32 s24, s24, 0x40080
	s_addc_u32 s25, s25, 0
	s_add_i32 s26, s52, s2
	global_load_lds_dwordx4 v130, s[100:101]
	s_mov_b32 m0, s26
	s_nop 0
	global_load_lds_dwordx4 v0, s[24:25]
	s_add_i32 m0, s26, 0x2000
	s_nop 0
	global_load_lds_dwordx4 v130, s[24:25]
	s_mov_b32 m0, s37
	s_nop 0
	global_load_lds_dwordx4 v134, s[98:99]
	s_mov_b32 m0, s38
	s_nop 0
	global_load_lds_dwordx4 v132, s[98:99]
	s_waitcnt vmcnt(8)
	s_waitcnt lgkmcnt(0)
	s_barrier
; #define PG8_MMA(ai, bj, At, Bt) do { __builtin_amdgcn_s_setprio(1); _Pragma("unroll") for (int m = 0; m < 4; ++m) _Pragma("unroll") for (int n = 0; n < 2; ++n) _Pragma("unroll") for (int k = 0; k < 2; ++k) \
;         acc[ai][bj][m][n] = __builtin_amdgcn_mfma_f32_16x16x32_bf16(Bt[n][k], At[m][k], acc[ai][bj][m][n], 0, 0, 0); __builtin_amdgcn_s_setprio(0); } while (0)
; #define PG8_WAIT_V(n) asm volatile("s_waitcnt vmcnt(" #n ")" ::: "memory")
; #define PG8_WAIT_L(n) asm volatile("s_waitcnt lgkmcnt(" #n ")" ::: "memory")
; #define PG8_BAR __builtin_amdgcn_s_barrier()
; #define PG8_SCHED __builtin_amdgcn_sched_barrier(0)
; template <class Epi, class Sched, bool ALIGN_EPI = false, bool SP2 = false>
; __device__ __forceinline__ void gemm_phase(PG8_LAS unsigned char* lds, const Gemm g, const Sched& S, const Epi& E) {
;     ...
;             PG8_WAIT_V(8); PG8_WAIT_L(0); PG8_BAR; PG8_MMA(1, 0, At, B0); PG8_MMA(1, 1, At, B1); PG8_BAR; PG8_SCHED;
; __device__ __forceinline__ float row_rstd(const float* rsp, int row, int fq) {
;     const f32x4 v = *(const f32x4*)(rsp + (size_t)row * 16 + 4 * fq);
;     float s = (v[0] + v[1]) + (v[2] + v[3]); s += __shfl_xor(s, 16); s += __shfl_xor(s, 32);
;     return rsqrtf(s * (1.0f / 1024.0f) + RMS_EPS);
; }
;     __device__ __forceinline__ void operator()(const f32x4 (&acc)[2][2][4][2], const Unit& u, int wr, int wc, int fr, int fq) const {
;         const int row0 = u.pm * BM + wr * 64 + fr, col0 = u.pn * HALF + wc * 32 + 8 * fq;
; #pragma unroll
;         for (int ai = 0; ai < 2; ++ai)
; #pragma unroll
;             for (int m = 0; m < 4; ++m) {
;                 const int row = row0 + ai * HALF + m * 16; const float rs = row_rstd(rsp, row, fq);
	s_setprio 1
	s_waitcnt lgkmcnt(0)
	v_mfma_f32_16x16x32_bf16 v[62:65], v[142:145], v[196:199], v[62:65]
	v_mfma_f32_16x16x32_bf16 v[54:57], v[172:175], v[196:199], v[54:57]
	v_mfma_f32_16x16x32_bf16 v[46:49], v[142:145], v[218:221], v[46:49]
	v_mfma_f32_16x16x32_bf16 v[38:41], v[172:175], v[218:221], v[38:41]
	v_mfma_f32_16x16x32_bf16 v[30:33], v[142:145], v[226:229], v[30:33]
	v_mfma_f32_16x16x32_bf16 v[22:25], v[172:175], v[226:229], v[22:25]
	v_mfma_f32_16x16x32_bf16 v[14:17], v[142:145], v[234:237], v[14:17]
	v_mfma_f32_16x16x32_bf16 v[6:9], v[172:175], v[234:237], v[6:9]
	v_mfma_f32_16x16x32_bf16 v[62:65], v[152:155], v[214:217], v[62:65]
	v_mfma_f32_16x16x32_bf16 v[54:57], v[176:179], v[214:217], v[54:57]
	v_mfma_f32_16x16x32_bf16 v[46:49], v[152:155], v[222:225], v[46:49]
	v_mfma_f32_16x16x32_bf16 v[38:41], v[176:179], v[222:225], v[38:41]
	v_mfma_f32_16x16x32_bf16 v[30:33], v[152:155], v[230:233], v[30:33]
	v_mfma_f32_16x16x32_bf16 v[22:25], v[176:179], v[230:233], v[22:25]
	v_mfma_f32_16x16x32_bf16 v[14:17], v[152:155], v[238:241], v[14:17]
	v_mfma_f32_16x16x32_bf16 v[6:9], v[176:179], v[238:241], v[6:9]
	s_setprio 0
	s_setprio 1
	v_mfma_f32_16x16x32_bf16 v[58:61], v[180:183], v[196:199], v[58:61]
	v_mfma_f32_16x16x32_bf16 v[50:53], v[188:191], v[196:199], v[50:53]
	v_mfma_f32_16x16x32_bf16 v[42:45], v[180:183], v[218:221], v[42:45]
	v_mfma_f32_16x16x32_bf16 v[34:37], v[188:191], v[218:221], v[34:37]
	v_mfma_f32_16x16x32_bf16 v[26:29], v[180:183], v[226:229], v[26:29]
	v_mfma_f32_16x16x32_bf16 v[18:21], v[188:191], v[226:229], v[18:21]
	v_mfma_f32_16x16x32_bf16 v[10:13], v[180:183], v[234:237], v[10:13]
	v_mfma_f32_16x16x32_bf16 v[2:5], v[188:191], v[234:237], v[2:5]
	v_mfma_f32_16x16x32_bf16 v[58:61], v[184:187], v[214:217], v[58:61]
	v_mfma_f32_16x16x32_bf16 v[50:53], v[192:195], v[214:217], v[50:53]
	v_mfma_f32_16x16x32_bf16 v[42:45], v[184:187], v[222:225], v[42:45]
	v_mfma_f32_16x16x32_bf16 v[34:37], v[192:195], v[222:225], v[34:37]
	v_mfma_f32_16x16x32_bf16 v[26:29], v[184:187], v[230:233], v[26:29]
	v_mfma_f32_16x16x32_bf16 v[18:21], v[192:195], v[230:233], v[18:21]
	v_mfma_f32_16x16x32_bf16 v[10:13], v[184:187], v[238:241], v[10:13]
	v_mfma_f32_16x16x32_bf16 v[2:5], v[192:195], v[238:241], v[2:5]
	s_setprio 0
	s_barrier
	s_add_i32 s50, s50, 2
	s_add_u32 s22, s22, 0x100
	s_addc_u32 s23, s23, 0
	s_add_u32 s48, s48, 0x100
	s_addc_u32 s49, s49, 0
	s_cmp_gt_u32 s50, 13
	s_cbranch_scc0 .LBB0_493
	v_lshl_add_u32 v142, s45, 8, v148
	v_mov_b32_e32 v143, 0
	s_mov_b32 s26, 0x2000
	s_mov_b32 s27, 0
	v_lshlrev_b64 v[146:147], 6, v[142:143]
	v_lshl_add_u64 v[146:147], v[136:137], 0, v[146:147]
	v_lshl_add_u64 v[156:157], v[146:147], 0, s[26:27]
	global_load_dwordx4 v[172:175], v[146:147], off
	global_load_dwordx4 v[176:179], v[146:147], off offset:1024
	global_load_dwordx4 v[180:183], v[146:147], off offset:2048
	global_load_dwordx4 v[184:187], v[146:147], off offset:3072
	global_load_dwordx4 v[188:191], v[156:157], off
	global_load_dwordx4 v[192:195], v[156:157], off offset:1024
	global_load_dwordx4 v[196:199], v[156:157], off offset:2048
	global_load_dwordx4 v[214:217], v[156:157], off offset:3072
	v_xor_b32_e32 v152, 16, v201
	v_xor_b32_e32 v153, 32, v201
	v_lshlrev_b32_e32 v152, 2, v152
	v_lshlrev_b32_e32 v153, 2, v153
	v_lshl_or_b32 v144, s44, 7, v150
	v_mov_b32_e32 v145, 0
	v_mov_b32_e32 v238, s0
	v_mov_b32_e32 v239, s1
	v_mad_i64_i32 v[236:237], s[22:23], v142, s93, v[238:239]
	v_lshlrev_b64 v[240:241], 1, v[144:145]
	v_mov_b32_e32 v234, 1.0
	v_mov_b32_e32 v235, 1.0
	v_lshl_add_u64 v[236:237], v[236:237], 0, v[240:241]
	s_mov_b32 s26, 0x16000
	s_mov_b32 s24, 0x6e000
	s_mov_b32 s25, 0
	s_and_b64 vcc, exec, s[12:13]
	s_cbranch_vccz .LBB0_496
	s_barrier

; __global__ void __launch_bounds__(512, 2) hybrid_fwd(Args a) {
	.amdhsa_kernel _Z10hybrid_fwd4Args
		.amdhsa_group_segment_fixed_size 0
		.amdhsa_private_segment_fixed_size 0
		.amdhsa_kernarg_size 448
		.amdhsa_user_sgpr_count 2
		.amdhsa_user_sgpr_dispatch_ptr 0
		.amdhsa_user_sgpr_queue_ptr 0
		.amdhsa_user_sgpr_kernarg_segment_ptr 1
		.amdhsa_user_sgpr_dispatch_id 0
		.amdhsa_user_sgpr_kernarg_preload_length 0
		.amdhsa_user_sgpr_kernarg_preload_offset 0
		.amdhsa_user_sgpr_private_segment_size 0
		.amdhsa_uses_dynamic_stack 0
		.amdhsa_enable_private_segment 0
		.amdhsa_system_sgpr_workgroup_id_x 1
		.amdhsa_system_sgpr_workgroup_id_y 0
		.amdhsa_system_sgpr_workgroup_id_z 0
		.amdhsa_system_sgpr_workgroup_info 0
		.amdhsa_system_vgpr_workitem_id 2
		.amdhsa_next_free_vgpr 253
		.amdhsa_next_free_sgpr 102
		.amdhsa_accum_offset 256
		.amdhsa_reserve_vcc 1
		.amdhsa_float_round_mode_32 0
		.amdhsa_float_round_mode_16_64 0
		.amdhsa_float_denorm_mode_32 3
		.amdhsa_float_denorm_mode_16_64 3
		.amdhsa_dx10_clamp 1
		.amdhsa_ieee_mode 1
		.amdhsa_fp16_overflow 0
		.amdhsa_tg_split 0
		.amdhsa_exception_fp_ieee_invalid_op 0
		.amdhsa_exception_fp_denorm_src 0
		.amdhsa_exception_fp_ieee_div_zero 0
		.amdhsa_exception_fp_ieee_overflow 0
		.amdhsa_exception_fp_ieee_underflow 0
		.amdhsa_exception_fp_ieee_inexact 0
		.amdhsa_exception_int_div_zero 0
	.end_amdhsa_kernel

; __global__ void __launch_bounds__(512, 2) hybrid_fwd(Args a) {
amdhsa.kernels:
  - .agpr_count:     0
    .args:
      - .offset:         0
        .size:           192
        .value_kind:     by_value
      - .offset:         192
        .size:           4
        .value_kind:     hidden_block_count_x
      - .offset:         196
        .size:           4
        .value_kind:     hidden_block_count_y
      - .offset:         200
        .size:           4
        .value_kind:     hidden_block_count_z
      - .offset:         204
        .size:           2
        .value_kind:     hidden_group_size_x
      - .offset:         206
        .size:           2
        .value_kind:     hidden_group_size_y
      - .offset:         208
        .size:           2
        .value_kind:     hidden_group_size_z
      - .offset:         210
        .size:           2
        .value_kind:     hidden_remainder_x
      - .offset:         212
        .size:           2
        .value_kind:     hidden_remainder_y
      - .offset:         214
        .size:           2
        .value_kind:     hidden_remainder_z
      - .offset:         232
        .size:           8
        .value_kind:     hidden_global_offset_x
      - .offset:         240
        .size:           8
        .value_kind:     hidden_global_offset_y
      - .offset:         248
        .size:           8
        .value_kind:     hidden_global_offset_z
      - .offset:         256
        .size:           2
        .value_kind:     hidden_grid_dims
      - .offset:         280
        .size:           8
        .value_kind:     hidden_multigrid_sync_arg
      - .offset:         312
        .size:           4
        .value_kind:     hidden_dynamic_lds_size
    .group_segment_fixed_size: 0
    .kernarg_segment_align: 8
    .kernarg_segment_size: 448
    .language:       OpenCL C
    .language_version:
      - 2
      - 0
    .max_flat_workgroup_size: 512
    .name:           _Z10hybrid_fwd4Args
    .private_segment_fixed_size: 0
    .sgpr_count:     108
    .sgpr_spill_count: 136
    .symbol:         _Z10hybrid_fwd4Args.kd
    .uniform_work_group_size: 1
    .uses_dynamic_stack: false
    .vgpr_count:     253
    .vgpr_spill_count: 0
    .wavefront_size: 64
